# stack11 plus write-through (sc1) on the P0 converted-weight stores and on the QKV, conv-in and UV GEMM output stores
# baseline (speedup 1.0000x reference)
.LBB0_1265:
	v_lshl_add_u32 v148, s22, 8, v1
	v_ashrrev_i32_e32 v149, 31, v148
	v_or_b32_e32 v154, 16, v148
	v_or_b32_e32 v152, 32, v148
	v_or_b32_e32 v150, 48, v148
	s_cmp_gt_i32 s50, 15
	v_lshlrev_b64 v[156:157], 12, v[148:149]
	s_mov_b64 s[22:23], -1
	v_ashrrev_i32_e32 v155, 31, v154
	v_ashrrev_i32_e32 v153, 31, v152
	v_ashrrev_i32_e32 v151, 31, v150
	s_cbranch_scc0 .LBB0_1268
	v_lshl_add_u32 v138, s50, 8, v161
	v_lshl_add_u64 v[158:159], s[58:59], 0, v[156:157]
	v_lshlrev_b64 v[174:175], 1, v[138:139]
	v_lshl_add_u64 v[158:159], v[158:159], 0, v[174:175]
	v_cvt_pk_bf16_f32 v170, v126, v127
	v_cvt_pk_bf16_f32 v171, v128, v129
	v_cvt_pk_bf16_f32 v172, v122, v123
	v_cvt_pk_bf16_f32 v173, v124, v125
	global_store_dwordx4 v[158:159], v[170:173], off sc1
	s_mov_b64 s[22:23], 0x80000
	s_mov_b32 s15, 0xb0000
	v_cvt_pk_bf16_f32 v170, v114, v115
	v_cvt_pk_bf16_f32 v171, v116, v117
	v_cvt_pk_bf16_f32 v172, v106, v107
	v_cvt_pk_bf16_f32 v173, v108, v109
	global_store_dwordx4 v[158:159], v[170:173], off offset:256 sc1
	s_nop 1
	v_lshlrev_b64 v[170:171], 12, v[154:155]
	v_lshl_add_u64 v[170:171], s[58:59], 0, v[170:171]
	v_lshl_add_u64 v[176:177], v[170:171], 0, v[174:175]
	v_cvt_pk_bf16_f32 v170, v118, v119
	v_cvt_pk_bf16_f32 v171, v120, v121
	v_cvt_pk_bf16_f32 v172, v110, v111
	v_cvt_pk_bf16_f32 v173, v112, v113
	global_store_dwordx4 v[176:177], v[170:173], off sc1
	s_nop 1
	v_cvt_pk_bf16_f32 v170, v98, v99
	v_cvt_pk_bf16_f32 v171, v100, v101
	v_cvt_pk_bf16_f32 v172, v90, v91
	v_cvt_pk_bf16_f32 v173, v92, v93
	global_store_dwordx4 v[176:177], v[170:173], off offset:256 sc1
	s_nop 1
	v_lshlrev_b64 v[170:171], 12, v[152:153]
	v_lshl_add_u64 v[170:171], s[58:59], 0, v[170:171]
	v_lshl_add_u64 v[176:177], v[170:171], 0, v[174:175]
	v_cvt_pk_bf16_f32 v170, v102, v103
	v_cvt_pk_bf16_f32 v171, v104, v105
	v_cvt_pk_bf16_f32 v172, v94, v95
	v_cvt_pk_bf16_f32 v173, v96, v97
	global_store_dwordx4 v[176:177], v[170:173], off sc1
	s_nop 1
	v_cvt_pk_bf16_f32 v170, v82, v83
	v_cvt_pk_bf16_f32 v171, v84, v85
	v_cvt_pk_bf16_f32 v172, v74, v75
	v_cvt_pk_bf16_f32 v173, v76, v77
	global_store_dwordx4 v[176:177], v[170:173], off offset:256 sc1
	v_add_co_u32_e32 v176, vcc, s47, v158
	s_nop 0
	v_lshlrev_b64 v[170:171], 12, v[150:151]
	v_lshl_add_u64 v[170:171], s[58:59], 0, v[170:171]
	v_lshl_add_u64 v[174:175], v[170:171], 0, v[174:175]
	v_cvt_pk_bf16_f32 v170, v86, v87
	v_cvt_pk_bf16_f32 v171, v88, v89
	v_cvt_pk_bf16_f32 v172, v78, v79
	v_cvt_pk_bf16_f32 v173, v80, v81
	global_store_dwordx4 v[174:175], v[170:173], off sc1
	v_addc_co_u32_e32 v177, vcc, 0, v159, vcc
	s_nop 0
	v_cvt_pk_bf16_f32 v170, v70, v71
	v_cvt_pk_bf16_f32 v171, v72, v73
	v_cvt_pk_bf16_f32 v172, v66, v67
	v_cvt_pk_bf16_f32 v173, v68, v69
	global_store_dwordx4 v[174:175], v[170:173], off offset:256 sc1
	v_lshl_add_u64 v[174:175], v[158:159], 0, s[22:23]
	s_mov_b64 s[22:23], 0x90000
	v_cvt_pk_bf16_f32 v170, v62, v63
	v_cvt_pk_bf16_f32 v171, v64, v65
	v_cvt_pk_bf16_f32 v172, v58, v59
	v_cvt_pk_bf16_f32 v173, v60, v61
	global_store_dwordx4 v[176:177], v[170:173], off sc1
	v_add_co_u32_e32 v176, vcc, s48, v158
	s_nop 0
	v_cvt_pk_bf16_f32 v170, v54, v55
	v_cvt_pk_bf16_f32 v171, v56, v57
	v_cvt_pk_bf16_f32 v172, v46, v47
	v_cvt_pk_bf16_f32 v173, v48, v49
	global_store_dwordx4 v[174:175], v[170:173], off offset:256 sc1
	v_addc_co_u32_e32 v177, vcc, 0, v159, vcc
	s_nop 0
	v_cvt_pk_bf16_f32 v170, v50, v51
	v_cvt_pk_bf16_f32 v171, v52, v53
	v_cvt_pk_bf16_f32 v172, v42, v43
	v_cvt_pk_bf16_f32 v173, v44, v45
	v_lshl_add_u64 v[174:175], v[158:159], 0, s[22:23]
	global_store_dwordx4 v[176:177], v[170:173], off sc1
	s_mov_b64 s[22:23], 0xa0000
	v_add_co_u32_e32 v176, vcc, s49, v158
	v_cvt_pk_bf16_f32 v170, v34, v35
	v_cvt_pk_bf16_f32 v171, v36, v37
	v_cvt_pk_bf16_f32 v172, v26, v27
	v_cvt_pk_bf16_f32 v173, v28, v29
	global_store_dwordx4 v[174:175], v[170:173], off offset:256 sc1
	v_lshl_add_u64 v[174:175], v[158:159], 0, s[22:23]
	v_addc_co_u32_e32 v177, vcc, 0, v159, vcc
	v_cvt_pk_bf16_f32 v170, v38, v39
	v_cvt_pk_bf16_f32 v171, v40, v41
	v_cvt_pk_bf16_f32 v172, v30, v31
	v_cvt_pk_bf16_f32 v173, v32, v33
	s_mov_b64 s[22:23], 0xb0000
	global_store_dwordx4 v[176:177], v[170:173], off sc1
	s_nop 1
	v_cvt_pk_bf16_f32 v170, v18, v19
	v_cvt_pk_bf16_f32 v171, v20, v21
	v_cvt_pk_bf16_f32 v172, v10, v11
	v_cvt_pk_bf16_f32 v173, v12, v13
	global_store_dwordx4 v[174:175], v[170:173], off offset:256 sc1
	v_lshl_add_u64 v[174:175], v[158:159], 0, s[22:23]
	v_add_co_u32_e32 v158, vcc, s15, v158
	v_cvt_pk_bf16_f32 v170, v22, v23
	v_cvt_pk_bf16_f32 v171, v24, v25
	v_cvt_pk_bf16_f32 v172, v14, v15
	v_cvt_pk_bf16_f32 v173, v16, v17
	s_nop 1
	v_addc_co_u32_e32 v159, vcc, 0, v159, vcc
	global_store_dwordx4 v[158:159], v[170:173], off sc1
	s_nop 1
	v_cvt_pk_bf16_f32 v170, v6, v7
	v_cvt_pk_bf16_f32 v171, v8, v9
	v_cvt_pk_bf16_f32 v172, v2, v3
	v_cvt_pk_bf16_f32 v173, v4, v5
	global_store_dwordx4 v[174:175], v[170:173], off offset:256 sc1
	s_cbranch_execz .LBB0_1269

.LBB0_1269:
	v_lshl_or_b32 v158, s50, 7, v160
	v_ashrrev_i32_e32 v159, 31, v158
	v_lshl_add_u64 v[156:157], s[84:85], 0, v[156:157]
	v_mul_f32_e32 v126, v126, v114
	v_mul_f32_e32 v127, v127, v115
	v_lshlrev_b64 v[114:115], 1, v[158:159]
	v_mul_f32_e32 v128, v128, v116
	v_mul_f32_e32 v129, v129, v117
	v_mul_f32_e32 v122, v122, v106
	v_mul_f32_e32 v123, v123, v107
	v_mul_f32_e32 v109, v125, v109
	v_lshl_add_u64 v[116:117], v[156:157], 0, v[114:115]
	v_cvt_pk_bf16_f32 v106, v126, v127
	v_cvt_pk_bf16_f32 v107, v128, v129
	v_mul_f32_e32 v124, v124, v108
	v_cvt_pk_bf16_f32 v108, v122, v123
	v_cvt_pk_bf16_f32 v109, v124, v109
	global_store_dwordx4 v[116:117], v[106:109], off sc1
	v_mul_f32_e32 v100, v120, v100
	v_mul_f32_e32 v101, v121, v101
	v_lshlrev_b64 v[106:107], 12, v[154:155]
	v_lshl_add_u64 v[106:107], s[84:85], 0, v[106:107]
	v_mul_f32_e32 v108, v118, v98
	v_mul_f32_e32 v109, v119, v99
	v_mul_f32_e32 v110, v110, v90
	v_mul_f32_e32 v111, v111, v91
	v_mul_f32_e32 v93, v113, v93
	v_lshl_add_u64 v[98:99], v[106:107], 0, v[114:115]
	v_cvt_pk_bf16_f32 v90, v108, v109
	v_cvt_pk_bf16_f32 v91, v100, v101
	v_mul_f32_e32 v112, v112, v92
	v_cvt_pk_bf16_f32 v92, v110, v111
	v_cvt_pk_bf16_f32 v93, v112, v93
	global_store_dwordx4 v[98:99], v[90:93], off sc1
	v_mul_f32_e32 v84, v104, v84
	v_mul_f32_e32 v85, v105, v85
	v_lshlrev_b64 v[90:91], 12, v[152:153]
	v_lshl_add_u64 v[90:91], s[84:85], 0, v[90:91]
	v_mul_f32_e32 v92, v102, v82
	v_mul_f32_e32 v93, v103, v83
	v_mul_f32_e32 v94, v94, v74
	v_mul_f32_e32 v95, v95, v75
	v_mul_f32_e32 v77, v97, v77
	v_lshl_add_u64 v[82:83], v[90:91], 0, v[114:115]
	v_cvt_pk_bf16_f32 v74, v92, v93
	v_cvt_pk_bf16_f32 v75, v84, v85
	v_mul_f32_e32 v96, v96, v76
	v_cvt_pk_bf16_f32 v76, v94, v95
	v_cvt_pk_bf16_f32 v77, v96, v77
	global_store_dwordx4 v[82:83], v[74:77], off sc1
	v_mul_f32_e32 v69, v81, v69
	v_mul_f32_e32 v54, v62, v54
	v_lshlrev_b64 v[74:75], 12, v[150:151]
	v_lshl_add_u64 v[74:75], s[84:85], 0, v[74:75]
	v_mul_f32_e32 v76, v86, v70
	v_mul_f32_e32 v77, v87, v71
	v_lshl_add_u64 v[70:71], v[74:75], 0, v[114:115]
	v_mul_f32_e32 v55, v63, v55
	v_mul_f32_e32 v72, v88, v72
	v_mul_f32_e32 v73, v89, v73
	v_mul_f32_e32 v78, v78, v66
	v_mul_f32_e32 v79, v79, v67
	v_mul_f32_e32 v80, v80, v68
	v_cvt_pk_bf16_f32 v66, v76, v77
	v_cvt_pk_bf16_f32 v67, v72, v73
	v_cvt_pk_bf16_f32 v68, v78, v79
	v_cvt_pk_bf16_f32 v69, v80, v69
	global_store_dwordx4 v[70:71], v[66:69], off sc1
	v_mul_f32_e32 v58, v58, v46
	v_cvt_pk_bf16_f32 v46, v54, v55
	v_lshlrev_b64 v[54:55], 12, v[148:149]
	v_lshl_add_u64 v[54:55], s[84:85], 0, v[54:55]
	v_mul_f32_e32 v56, v64, v56
	v_lshl_add_u64 v[54:55], v[54:55], 0, v[114:115]
	v_mul_f32_e32 v57, v65, v57
	v_mul_f32_e32 v59, v59, v47
	v_cvt_pk_bf16_f32 v47, v56, v57
	v_add_co_u32_e32 v56, vcc, s47, v54
	v_mul_f32_e32 v49, v61, v49
	s_nop 0
	v_addc_co_u32_e32 v57, vcc, 0, v55, vcc
	v_mul_f32_e32 v34, v50, v34
	v_mul_f32_e32 v60, v60, v48
	v_cvt_pk_bf16_f32 v48, v58, v59
	v_cvt_pk_bf16_f32 v49, v60, v49
	global_store_dwordx4 v[56:57], v[46:49], off sc1
	v_mul_f32_e32 v35, v51, v35
	v_mul_f32_e32 v42, v42, v26
	v_cvt_pk_bf16_f32 v26, v34, v35
	v_add_co_u32_e32 v34, vcc, s48, v54
	v_mul_f32_e32 v29, v45, v29
	s_nop 0
	v_addc_co_u32_e32 v35, vcc, 0, v55, vcc
	v_mul_f32_e32 v18, v38, v18
	v_mul_f32_e32 v36, v52, v36
	v_mul_f32_e32 v37, v53, v37
	v_mul_f32_e32 v43, v43, v27
	v_mul_f32_e32 v44, v44, v28
	v_cvt_pk_bf16_f32 v27, v36, v37
	v_cvt_pk_bf16_f32 v28, v42, v43
	v_cvt_pk_bf16_f32 v29, v44, v29
	global_store_dwordx4 v[34:35], v[26:29], off sc1
	v_mul_f32_e32 v19, v39, v19
	v_mul_f32_e32 v13, v33, v13
	v_mul_f32_e32 v26, v30, v10
	v_cvt_pk_bf16_f32 v10, v18, v19
	v_add_co_u32_e32 v18, vcc, s49, v54
	v_mul_f32_e32 v6, v22, v6
	s_nop 0
	v_addc_co_u32_e32 v19, vcc, 0, v55, vcc
	v_mul_f32_e32 v20, v40, v20
	v_mul_f32_e32 v21, v41, v21
	v_mul_f32_e32 v27, v31, v11
	v_mul_f32_e32 v28, v32, v12
	v_cvt_pk_bf16_f32 v11, v20, v21
	v_cvt_pk_bf16_f32 v12, v26, v27
	v_cvt_pk_bf16_f32 v13, v28, v13
	global_store_dwordx4 v[18:19], v[10:13], off sc1
	v_mul_f32_e32 v7, v23, v7
	v_mul_f32_e32 v5, v17, v5
	v_mul_f32_e32 v10, v14, v2
	v_cvt_pk_bf16_f32 v2, v6, v7
	v_add_co_u32_e32 v6, vcc, 0xb0000, v54
	v_mul_f32_e32 v8, v24, v8
	s_nop 0
	v_addc_co_u32_e32 v7, vcc, 0, v55, vcc
	v_mul_f32_e32 v9, v25, v9
	v_mul_f32_e32 v11, v15, v3
	v_mul_f32_e32 v12, v16, v4
	v_cvt_pk_bf16_f32 v3, v8, v9
	v_cvt_pk_bf16_f32 v4, v10, v11
	v_cvt_pk_bf16_f32 v5, v12, v5
	global_store_dwordx4 v[6:7], v[2:5], off sc1
	s_andn2_b64 vcc, exec, s[4:5]
	s_mov_b64 s[4:5], -1
	s_cbranch_vccnz .LBB0_1258

.LBB0_3023:
	v_lshl_or_b32 v146, s47, 8, v150
	v_lshl_add_u32 v156, s26, 8, v1
	v_ashrrev_i32_e32 v147, 31, v146
	v_lshl_add_u64 v[148:149], v[146:147], 1, s[30:31]
	v_mad_i64_i32 v[146:147], s[30:31], s28, v156, 0
	v_lshl_add_u64 v[158:159], v[146:147], 1, v[148:149]
	v_pk_mul_f32 v[160:161], v[128:129], v[128:129]
	v_pk_mul_f32 v[162:163], v[126:127], v[126:127]
	v_mov_b64_e32 v[146:147], s[14:15]
	v_pk_mul_f32 v[164:165], v[124:125], v[124:125]
	v_pk_mul_f32 v[170:171], v[122:123], v[122:123]
	v_pk_fma_f32 v[162:163], v[162:163], s[12:13], v[146:147] op_sel_hi:[1,0,0] neg_lo:[1,0,0] neg_hi:[1,0,0]
	v_pk_fma_f32 v[160:161], v[160:161], s[12:13], v[146:147] op_sel_hi:[1,0,0] neg_lo:[1,0,0] neg_hi:[1,0,0]
	v_pk_fma_f32 v[170:171], v[170:171], s[12:13], v[146:147] op_sel_hi:[1,0,0] neg_lo:[1,0,0] neg_hi:[1,0,0]
	v_pk_fma_f32 v[164:165], v[164:165], s[12:13], v[146:147] op_sel_hi:[1,0,0] neg_lo:[1,0,0] neg_hi:[1,0,0]
	v_pk_mul_f32 v[162:163], v[126:127], v[162:163]
	v_pk_mul_f32 v[160:161], v[128:129], v[160:161]
	v_pk_mul_f32 v[170:171], v[122:123], v[170:171]
	v_pk_mul_f32 v[164:165], v[124:125], v[164:165]
	v_exp_f32_e32 v162, v162
	v_exp_f32_e32 v163, v163
	v_exp_f32_e32 v160, v160
	v_exp_f32_e32 v161, v161
	v_exp_f32_e32 v170, v170
	v_exp_f32_e32 v171, v171
	v_exp_f32_e32 v164, v164
	v_exp_f32_e32 v165, v165
	v_pk_add_f32 v[162:163], v[162:163], 1.0 op_sel_hi:[1,0]
	v_pk_add_f32 v[160:161], v[160:161], 1.0 op_sel_hi:[1,0]
	v_pk_add_f32 v[170:171], v[170:171], 1.0 op_sel_hi:[1,0]
	v_pk_add_f32 v[164:165], v[164:165], 1.0 op_sel_hi:[1,0]
	v_rcp_f32_e32 v162, v162
	v_rcp_f32_e32 v163, v163
	v_rcp_f32_e32 v160, v160
	v_rcp_f32_e32 v161, v161
	v_rcp_f32_e32 v170, v170
	v_rcp_f32_e32 v171, v171
	v_rcp_f32_e32 v164, v164
	v_rcp_f32_e32 v165, v165
	v_pk_mul_f32 v[126:127], v[126:127], v[162:163]
	v_pk_mul_f32 v[128:129], v[128:129], v[160:161]
	v_pk_mul_f32 v[160:161], v[122:123], v[170:171]
	v_pk_mul_f32 v[162:163], v[124:125], v[164:165]
	v_cvt_pk_bf16_f32 v122, v126, v127
	v_cvt_pk_bf16_f32 v123, v128, v129
	v_cvt_pk_bf16_f32 v124, v160, v161
	v_pk_mul_f32 v[126:127], v[116:117], v[116:117]
	v_cvt_pk_bf16_f32 v125, v162, v163
	global_store_dwordx4 v[158:159], v[122:125], off sc1
	v_pk_mul_f32 v[128:129], v[114:115], v[114:115]
	v_pk_fma_f32 v[126:127], v[126:127], s[12:13], v[146:147] op_sel_hi:[1,0,0] neg_lo:[1,0,0] neg_hi:[1,0,0]
	v_pk_mul_f32 v[122:123], v[120:121], v[120:121]
	v_pk_mul_f32 v[124:125], v[118:119], v[118:119]
	v_pk_fma_f32 v[122:123], v[122:123], s[12:13], v[146:147] op_sel_hi:[1,0,0] neg_lo:[1,0,0] neg_hi:[1,0,0]
	v_pk_fma_f32 v[124:125], v[124:125], s[12:13], v[146:147] op_sel_hi:[1,0,0] neg_lo:[1,0,0] neg_hi:[1,0,0]
	v_pk_fma_f32 v[128:129], v[128:129], s[12:13], v[146:147] op_sel_hi:[1,0,0] neg_lo:[1,0,0] neg_hi:[1,0,0]
	v_pk_mul_f32 v[124:125], v[118:119], v[124:125]
	v_pk_mul_f32 v[122:123], v[120:121], v[122:123]
	v_pk_mul_f32 v[128:129], v[114:115], v[128:129]
	v_pk_mul_f32 v[126:127], v[116:117], v[126:127]
	v_exp_f32_e32 v124, v124
	v_exp_f32_e32 v125, v125
	v_exp_f32_e32 v122, v122
	v_exp_f32_e32 v123, v123
	v_exp_f32_e32 v128, v128
	v_exp_f32_e32 v129, v129
	v_exp_f32_e32 v126, v126
	v_exp_f32_e32 v127, v127
	v_pk_add_f32 v[124:125], v[124:125], 1.0 op_sel_hi:[1,0]
	v_pk_add_f32 v[122:123], v[122:123], 1.0 op_sel_hi:[1,0]
	v_pk_add_f32 v[128:129], v[128:129], 1.0 op_sel_hi:[1,0]
	v_pk_add_f32 v[126:127], v[126:127], 1.0 op_sel_hi:[1,0]
	v_rcp_f32_e32 v124, v124
	v_rcp_f32_e32 v125, v125
	v_rcp_f32_e32 v122, v122
	v_rcp_f32_e32 v123, v123
	v_rcp_f32_e32 v128, v128
	v_rcp_f32_e32 v129, v129
	v_rcp_f32_e32 v126, v126
	v_rcp_f32_e32 v127, v127
	v_pk_mul_f32 v[118:119], v[118:119], v[124:125]
	v_pk_mul_f32 v[120:121], v[120:121], v[122:123]
	v_pk_mul_f32 v[122:123], v[114:115], v[128:129]
	v_pk_mul_f32 v[124:125], v[116:117], v[126:127]
	v_cvt_pk_bf16_f32 v114, v118, v119
	v_cvt_pk_bf16_f32 v115, v120, v121
	v_cvt_pk_bf16_f32 v116, v122, v123
	v_pk_mul_f32 v[118:119], v[110:111], v[110:111]
	v_cvt_pk_bf16_f32 v117, v124, v125
	global_store_dwordx4 v[158:159], v[114:117], off offset:256 sc1
	v_pk_mul_f32 v[120:121], v[108:109], v[108:109]
	v_pk_mul_f32 v[122:123], v[106:107], v[106:107]
	v_pk_mul_f32 v[116:117], v[112:113], v[112:113]
	v_pk_fma_f32 v[118:119], v[118:119], s[12:13], v[146:147] op_sel_hi:[1,0,0] neg_lo:[1,0,0] neg_hi:[1,0,0]
	v_pk_fma_f32 v[116:117], v[116:117], s[12:13], v[146:147] op_sel_hi:[1,0,0] neg_lo:[1,0,0] neg_hi:[1,0,0]
	v_pk_fma_f32 v[122:123], v[122:123], s[12:13], v[146:147] op_sel_hi:[1,0,0] neg_lo:[1,0,0] neg_hi:[1,0,0]
	v_pk_fma_f32 v[120:121], v[120:121], s[12:13], v[146:147] op_sel_hi:[1,0,0] neg_lo:[1,0,0] neg_hi:[1,0,0]
	v_pk_mul_f32 v[118:119], v[110:111], v[118:119]
	v_pk_mul_f32 v[116:117], v[112:113], v[116:117]
	v_pk_mul_f32 v[122:123], v[106:107], v[122:123]
	v_pk_mul_f32 v[120:121], v[108:109], v[120:121]
	v_exp_f32_e32 v118, v118
	v_exp_f32_e32 v119, v119
	v_exp_f32_e32 v116, v116
	v_exp_f32_e32 v117, v117
	v_exp_f32_e32 v122, v122
	v_exp_f32_e32 v123, v123
	v_exp_f32_e32 v120, v120
	v_exp_f32_e32 v121, v121
	v_pk_add_f32 v[118:119], v[118:119], 1.0 op_sel_hi:[1,0]
	v_pk_add_f32 v[116:117], v[116:117], 1.0 op_sel_hi:[1,0]
	v_pk_add_f32 v[122:123], v[122:123], 1.0 op_sel_hi:[1,0]
	v_pk_add_f32 v[120:121], v[120:121], 1.0 op_sel_hi:[1,0]
	v_rcp_f32_e32 v118, v118
	v_rcp_f32_e32 v119, v119
	v_rcp_f32_e32 v116, v116
	v_rcp_f32_e32 v117, v117
	v_rcp_f32_e32 v122, v122
	v_rcp_f32_e32 v123, v123
	v_rcp_f32_e32 v120, v120
	v_rcp_f32_e32 v121, v121
	v_or_b32_e32 v114, 16, v156
	v_mad_i64_i32 v[114:115], s[30:31], s28, v114, 0
	v_lshl_add_u64 v[114:115], v[114:115], 1, v[148:149]
	v_pk_mul_f32 v[110:111], v[110:111], v[118:119]
	v_pk_mul_f32 v[112:113], v[112:113], v[116:117]
	v_pk_mul_f32 v[116:117], v[106:107], v[122:123]
	v_pk_mul_f32 v[118:119], v[108:109], v[120:121]
	v_cvt_pk_bf16_f32 v106, v110, v111
	v_cvt_pk_bf16_f32 v107, v112, v113
	v_cvt_pk_bf16_f32 v108, v116, v117
	v_pk_mul_f32 v[110:111], v[100:101], v[100:101]
	v_cvt_pk_bf16_f32 v109, v118, v119
	global_store_dwordx4 v[114:115], v[106:109], off sc1
	v_pk_mul_f32 v[112:113], v[98:99], v[98:99]
	v_pk_fma_f32 v[110:111], v[110:111], s[12:13], v[146:147] op_sel_hi:[1,0,0] neg_lo:[1,0,0] neg_hi:[1,0,0]
	v_pk_mul_f32 v[106:107], v[104:105], v[104:105]
	v_pk_mul_f32 v[108:109], v[102:103], v[102:103]
	v_pk_fma_f32 v[106:107], v[106:107], s[12:13], v[146:147] op_sel_hi:[1,0,0] neg_lo:[1,0,0] neg_hi:[1,0,0]
	v_pk_fma_f32 v[108:109], v[108:109], s[12:13], v[146:147] op_sel_hi:[1,0,0] neg_lo:[1,0,0] neg_hi:[1,0,0]
	v_pk_fma_f32 v[112:113], v[112:113], s[12:13], v[146:147] op_sel_hi:[1,0,0] neg_lo:[1,0,0] neg_hi:[1,0,0]
	v_pk_mul_f32 v[108:109], v[102:103], v[108:109]
	v_pk_mul_f32 v[106:107], v[104:105], v[106:107]
	v_pk_mul_f32 v[112:113], v[98:99], v[112:113]
	v_pk_mul_f32 v[110:111], v[100:101], v[110:111]
	v_exp_f32_e32 v108, v108
	v_exp_f32_e32 v109, v109
	v_exp_f32_e32 v106, v106
	v_exp_f32_e32 v107, v107
	v_exp_f32_e32 v112, v112
	v_exp_f32_e32 v113, v113
	v_exp_f32_e32 v110, v110
	v_exp_f32_e32 v111, v111
	v_pk_add_f32 v[108:109], v[108:109], 1.0 op_sel_hi:[1,0]
	v_pk_add_f32 v[106:107], v[106:107], 1.0 op_sel_hi:[1,0]
	v_pk_add_f32 v[112:113], v[112:113], 1.0 op_sel_hi:[1,0]
	v_pk_add_f32 v[110:111], v[110:111], 1.0 op_sel_hi:[1,0]
	v_rcp_f32_e32 v108, v108
	v_rcp_f32_e32 v109, v109
	v_rcp_f32_e32 v106, v106
	v_rcp_f32_e32 v107, v107
	v_rcp_f32_e32 v112, v112
	v_rcp_f32_e32 v113, v113
	v_rcp_f32_e32 v110, v110
	v_rcp_f32_e32 v111, v111
	v_pk_mul_f32 v[102:103], v[102:103], v[108:109]
	v_pk_mul_f32 v[104:105], v[104:105], v[106:107]
	v_pk_mul_f32 v[106:107], v[98:99], v[112:113]
	v_pk_mul_f32 v[108:109], v[100:101], v[110:111]
	v_cvt_pk_bf16_f32 v98, v102, v103
	v_cvt_pk_bf16_f32 v99, v104, v105
	v_cvt_pk_bf16_f32 v100, v106, v107
	v_pk_mul_f32 v[102:103], v[94:95], v[94:95]
	v_cvt_pk_bf16_f32 v101, v108, v109
	global_store_dwordx4 v[114:115], v[98:101], off offset:256 sc1
	v_pk_mul_f32 v[104:105], v[92:93], v[92:93]
	v_pk_mul_f32 v[106:107], v[90:91], v[90:91]
	v_pk_mul_f32 v[100:101], v[96:97], v[96:97]
	v_pk_fma_f32 v[102:103], v[102:103], s[12:13], v[146:147] op_sel_hi:[1,0,0] neg_lo:[1,0,0] neg_hi:[1,0,0]
	v_pk_fma_f32 v[100:101], v[100:101], s[12:13], v[146:147] op_sel_hi:[1,0,0] neg_lo:[1,0,0] neg_hi:[1,0,0]
	v_pk_fma_f32 v[106:107], v[106:107], s[12:13], v[146:147] op_sel_hi:[1,0,0] neg_lo:[1,0,0] neg_hi:[1,0,0]
	v_pk_fma_f32 v[104:105], v[104:105], s[12:13], v[146:147] op_sel_hi:[1,0,0] neg_lo:[1,0,0] neg_hi:[1,0,0]
	v_pk_mul_f32 v[102:103], v[94:95], v[102:103]
	v_pk_mul_f32 v[100:101], v[96:97], v[100:101]
	v_pk_mul_f32 v[106:107], v[90:91], v[106:107]
	v_pk_mul_f32 v[104:105], v[92:93], v[104:105]
	v_exp_f32_e32 v102, v102
	v_exp_f32_e32 v103, v103
	v_exp_f32_e32 v100, v100
	v_exp_f32_e32 v101, v101
	v_exp_f32_e32 v106, v106
	v_exp_f32_e32 v107, v107
	v_exp_f32_e32 v104, v104
	v_exp_f32_e32 v105, v105
	v_pk_add_f32 v[102:103], v[102:103], 1.0 op_sel_hi:[1,0]
	v_pk_add_f32 v[100:101], v[100:101], 1.0 op_sel_hi:[1,0]
	v_pk_add_f32 v[106:107], v[106:107], 1.0 op_sel_hi:[1,0]
	v_pk_add_f32 v[104:105], v[104:105], 1.0 op_sel_hi:[1,0]
	v_rcp_f32_e32 v102, v102
	v_rcp_f32_e32 v103, v103
	v_rcp_f32_e32 v100, v100
	v_rcp_f32_e32 v101, v101
	v_rcp_f32_e32 v106, v106
	v_rcp_f32_e32 v107, v107
	v_rcp_f32_e32 v104, v104
	v_rcp_f32_e32 v105, v105
	v_or_b32_e32 v98, 32, v156
	v_mad_i64_i32 v[98:99], s[30:31], s28, v98, 0
	v_lshl_add_u64 v[98:99], v[98:99], 1, v[148:149]
	v_pk_mul_f32 v[94:95], v[94:95], v[102:103]
	v_pk_mul_f32 v[96:97], v[96:97], v[100:101]
	v_pk_mul_f32 v[100:101], v[90:91], v[106:107]
	v_pk_mul_f32 v[102:103], v[92:93], v[104:105]
	v_cvt_pk_bf16_f32 v90, v94, v95
	v_cvt_pk_bf16_f32 v91, v96, v97
	v_cvt_pk_bf16_f32 v92, v100, v101
	v_pk_mul_f32 v[94:95], v[84:85], v[84:85]
	v_cvt_pk_bf16_f32 v93, v102, v103
	global_store_dwordx4 v[98:99], v[90:93], off sc1
	v_pk_mul_f32 v[96:97], v[82:83], v[82:83]
	v_pk_fma_f32 v[94:95], v[94:95], s[12:13], v[146:147] op_sel_hi:[1,0,0] neg_lo:[1,0,0] neg_hi:[1,0,0]
	v_pk_mul_f32 v[90:91], v[88:89], v[88:89]
	v_pk_mul_f32 v[92:93], v[86:87], v[86:87]
	v_pk_fma_f32 v[90:91], v[90:91], s[12:13], v[146:147] op_sel_hi:[1,0,0] neg_lo:[1,0,0] neg_hi:[1,0,0]
	v_pk_fma_f32 v[92:93], v[92:93], s[12:13], v[146:147] op_sel_hi:[1,0,0] neg_lo:[1,0,0] neg_hi:[1,0,0]
	v_pk_fma_f32 v[96:97], v[96:97], s[12:13], v[146:147] op_sel_hi:[1,0,0] neg_lo:[1,0,0] neg_hi:[1,0,0]
	v_pk_mul_f32 v[92:93], v[86:87], v[92:93]
	v_pk_mul_f32 v[90:91], v[88:89], v[90:91]
	v_pk_mul_f32 v[96:97], v[82:83], v[96:97]
	v_pk_mul_f32 v[94:95], v[84:85], v[94:95]
	v_exp_f32_e32 v92, v92
	v_exp_f32_e32 v93, v93
	v_exp_f32_e32 v90, v90
	v_exp_f32_e32 v91, v91
	v_exp_f32_e32 v96, v96
	v_exp_f32_e32 v97, v97
	v_exp_f32_e32 v94, v94
	v_exp_f32_e32 v95, v95
	v_pk_add_f32 v[92:93], v[92:93], 1.0 op_sel_hi:[1,0]
	v_pk_add_f32 v[90:91], v[90:91], 1.0 op_sel_hi:[1,0]
	v_pk_add_f32 v[96:97], v[96:97], 1.0 op_sel_hi:[1,0]
	v_pk_add_f32 v[94:95], v[94:95], 1.0 op_sel_hi:[1,0]
	v_rcp_f32_e32 v92, v92
	v_rcp_f32_e32 v93, v93
	v_rcp_f32_e32 v90, v90
	v_rcp_f32_e32 v91, v91
	v_rcp_f32_e32 v96, v96
	v_rcp_f32_e32 v97, v97
	v_rcp_f32_e32 v94, v94
	v_rcp_f32_e32 v95, v95
	v_pk_mul_f32 v[86:87], v[86:87], v[92:93]
	v_pk_mul_f32 v[88:89], v[88:89], v[90:91]
	v_pk_mul_f32 v[90:91], v[82:83], v[96:97]
	v_pk_mul_f32 v[92:93], v[84:85], v[94:95]
	v_cvt_pk_bf16_f32 v82, v86, v87
	v_cvt_pk_bf16_f32 v83, v88, v89
	v_cvt_pk_bf16_f32 v84, v90, v91
	v_pk_mul_f32 v[86:87], v[78:79], v[78:79]
	v_cvt_pk_bf16_f32 v85, v92, v93
	global_store_dwordx4 v[98:99], v[82:85], off offset:256 sc1
	v_pk_mul_f32 v[88:89], v[76:77], v[76:77]
	v_pk_mul_f32 v[90:91], v[74:75], v[74:75]
	v_pk_mul_f32 v[84:85], v[80:81], v[80:81]
	v_pk_fma_f32 v[86:87], v[86:87], s[12:13], v[146:147] op_sel_hi:[1,0,0] neg_lo:[1,0,0] neg_hi:[1,0,0]
	v_pk_fma_f32 v[84:85], v[84:85], s[12:13], v[146:147] op_sel_hi:[1,0,0] neg_lo:[1,0,0] neg_hi:[1,0,0]
	v_pk_fma_f32 v[90:91], v[90:91], s[12:13], v[146:147] op_sel_hi:[1,0,0] neg_lo:[1,0,0] neg_hi:[1,0,0]
	v_pk_fma_f32 v[88:89], v[88:89], s[12:13], v[146:147] op_sel_hi:[1,0,0] neg_lo:[1,0,0] neg_hi:[1,0,0]
	v_pk_mul_f32 v[86:87], v[78:79], v[86:87]
	v_pk_mul_f32 v[84:85], v[80:81], v[84:85]
	v_pk_mul_f32 v[90:91], v[74:75], v[90:91]
	v_pk_mul_f32 v[88:89], v[76:77], v[88:89]
	v_exp_f32_e32 v86, v86
	v_exp_f32_e32 v87, v87
	v_exp_f32_e32 v84, v84
	v_exp_f32_e32 v85, v85
	v_exp_f32_e32 v90, v90
	v_exp_f32_e32 v91, v91
	v_exp_f32_e32 v88, v88
	v_exp_f32_e32 v89, v89
	v_pk_add_f32 v[86:87], v[86:87], 1.0 op_sel_hi:[1,0]
	v_pk_add_f32 v[84:85], v[84:85], 1.0 op_sel_hi:[1,0]
	v_pk_add_f32 v[90:91], v[90:91], 1.0 op_sel_hi:[1,0]
	v_pk_add_f32 v[88:89], v[88:89], 1.0 op_sel_hi:[1,0]
	v_rcp_f32_e32 v86, v86
	v_rcp_f32_e32 v87, v87
	v_rcp_f32_e32 v84, v84
	v_rcp_f32_e32 v85, v85
	v_rcp_f32_e32 v90, v90
	v_rcp_f32_e32 v91, v91
	v_rcp_f32_e32 v88, v88
	v_rcp_f32_e32 v89, v89
	v_or_b32_e32 v82, 48, v156
	v_mad_i64_i32 v[82:83], s[30:31], s28, v82, 0
	v_lshl_add_u64 v[82:83], v[82:83], 1, v[148:149]
	v_pk_mul_f32 v[78:79], v[78:79], v[86:87]
	v_pk_mul_f32 v[80:81], v[80:81], v[84:85]
	v_pk_mul_f32 v[84:85], v[74:75], v[90:91]
	v_pk_mul_f32 v[86:87], v[76:77], v[88:89]
	v_cvt_pk_bf16_f32 v74, v78, v79
	v_cvt_pk_bf16_f32 v75, v80, v81
	v_cvt_pk_bf16_f32 v76, v84, v85
	v_pk_mul_f32 v[78:79], v[68:69], v[68:69]
	v_cvt_pk_bf16_f32 v77, v86, v87
	global_store_dwordx4 v[82:83], v[74:77], off sc1
	v_pk_mul_f32 v[80:81], v[66:67], v[66:67]
	v_pk_fma_f32 v[78:79], v[78:79], s[12:13], v[146:147] op_sel_hi:[1,0,0] neg_lo:[1,0,0] neg_hi:[1,0,0]
	v_pk_mul_f32 v[74:75], v[72:73], v[72:73]
	v_pk_mul_f32 v[76:77], v[70:71], v[70:71]
	v_pk_fma_f32 v[74:75], v[74:75], s[12:13], v[146:147] op_sel_hi:[1,0,0] neg_lo:[1,0,0] neg_hi:[1,0,0]
	v_pk_fma_f32 v[76:77], v[76:77], s[12:13], v[146:147] op_sel_hi:[1,0,0] neg_lo:[1,0,0] neg_hi:[1,0,0]
	v_pk_fma_f32 v[80:81], v[80:81], s[12:13], v[146:147] op_sel_hi:[1,0,0] neg_lo:[1,0,0] neg_hi:[1,0,0]
	v_pk_mul_f32 v[76:77], v[70:71], v[76:77]
	v_pk_mul_f32 v[74:75], v[72:73], v[74:75]
	v_pk_mul_f32 v[80:81], v[66:67], v[80:81]
	v_pk_mul_f32 v[78:79], v[68:69], v[78:79]
	v_exp_f32_e32 v76, v76
	v_exp_f32_e32 v77, v77
	v_exp_f32_e32 v74, v74
	v_exp_f32_e32 v75, v75
	v_exp_f32_e32 v80, v80
	v_exp_f32_e32 v81, v81
	v_exp_f32_e32 v78, v78
	v_exp_f32_e32 v79, v79
	v_pk_add_f32 v[76:77], v[76:77], 1.0 op_sel_hi:[1,0]
	v_pk_add_f32 v[74:75], v[74:75], 1.0 op_sel_hi:[1,0]
	v_pk_add_f32 v[80:81], v[80:81], 1.0 op_sel_hi:[1,0]
	v_pk_add_f32 v[78:79], v[78:79], 1.0 op_sel_hi:[1,0]
	v_rcp_f32_e32 v76, v76
	v_rcp_f32_e32 v77, v77
	v_rcp_f32_e32 v74, v74
	v_rcp_f32_e32 v75, v75
	v_rcp_f32_e32 v80, v80
	v_rcp_f32_e32 v81, v81
	v_rcp_f32_e32 v78, v78
	v_rcp_f32_e32 v79, v79
	v_pk_mul_f32 v[70:71], v[70:71], v[76:77]
	v_pk_mul_f32 v[72:73], v[72:73], v[74:75]
	v_pk_mul_f32 v[74:75], v[66:67], v[80:81]
	v_pk_mul_f32 v[76:77], v[68:69], v[78:79]
	v_cvt_pk_bf16_f32 v66, v70, v71
	v_cvt_pk_bf16_f32 v67, v72, v73
	v_cvt_pk_bf16_f32 v68, v74, v75
	v_pk_mul_f32 v[70:71], v[62:63], v[62:63]
	v_cvt_pk_bf16_f32 v69, v76, v77
	global_store_dwordx4 v[82:83], v[66:69], off offset:256 sc1
	v_pk_mul_f32 v[72:73], v[60:61], v[60:61]
	v_pk_mul_f32 v[74:75], v[58:59], v[58:59]
	v_pk_mul_f32 v[68:69], v[64:65], v[64:65]
	v_pk_fma_f32 v[70:71], v[70:71], s[12:13], v[146:147] op_sel_hi:[1,0,0] neg_lo:[1,0,0] neg_hi:[1,0,0]
	v_pk_fma_f32 v[68:69], v[68:69], s[12:13], v[146:147] op_sel_hi:[1,0,0] neg_lo:[1,0,0] neg_hi:[1,0,0]
	v_pk_fma_f32 v[74:75], v[74:75], s[12:13], v[146:147] op_sel_hi:[1,0,0] neg_lo:[1,0,0] neg_hi:[1,0,0]
	v_pk_fma_f32 v[72:73], v[72:73], s[12:13], v[146:147] op_sel_hi:[1,0,0] neg_lo:[1,0,0] neg_hi:[1,0,0]
	v_pk_mul_f32 v[70:71], v[62:63], v[70:71]
	v_pk_mul_f32 v[68:69], v[64:65], v[68:69]
	v_pk_mul_f32 v[74:75], v[58:59], v[74:75]
	v_pk_mul_f32 v[72:73], v[60:61], v[72:73]
	v_exp_f32_e32 v70, v70
	v_exp_f32_e32 v71, v71
	v_exp_f32_e32 v68, v68
	v_exp_f32_e32 v69, v69
	v_exp_f32_e32 v74, v74
	v_exp_f32_e32 v75, v75
	v_exp_f32_e32 v72, v72
	v_exp_f32_e32 v73, v73
	v_pk_add_f32 v[70:71], v[70:71], 1.0 op_sel_hi:[1,0]
	v_pk_add_f32 v[68:69], v[68:69], 1.0 op_sel_hi:[1,0]
	v_pk_add_f32 v[74:75], v[74:75], 1.0 op_sel_hi:[1,0]
	v_pk_add_f32 v[72:73], v[72:73], 1.0 op_sel_hi:[1,0]
	v_rcp_f32_e32 v70, v70
	v_rcp_f32_e32 v71, v71
	v_rcp_f32_e32 v68, v68
	v_rcp_f32_e32 v69, v69
	v_rcp_f32_e32 v74, v74
	v_rcp_f32_e32 v75, v75
	v_rcp_f32_e32 v72, v72
	v_rcp_f32_e32 v73, v73
	v_add_u32_e32 v66, 0x80, v156
	v_mad_i64_i32 v[66:67], s[30:31], s28, v66, 0
	v_lshl_add_u64 v[66:67], v[66:67], 1, v[148:149]
	v_pk_mul_f32 v[62:63], v[62:63], v[70:71]
	v_pk_mul_f32 v[64:65], v[64:65], v[68:69]
	v_pk_mul_f32 v[68:69], v[58:59], v[74:75]
	v_pk_mul_f32 v[70:71], v[60:61], v[72:73]
	v_cvt_pk_bf16_f32 v58, v62, v63
	v_cvt_pk_bf16_f32 v59, v64, v65
	v_cvt_pk_bf16_f32 v60, v68, v69
	v_pk_mul_f32 v[62:63], v[52:53], v[52:53]
	v_cvt_pk_bf16_f32 v61, v70, v71
	global_store_dwordx4 v[66:67], v[58:61], off sc1
	v_pk_mul_f32 v[64:65], v[50:51], v[50:51]
	v_pk_fma_f32 v[62:63], v[62:63], s[12:13], v[146:147] op_sel_hi:[1,0,0] neg_lo:[1,0,0] neg_hi:[1,0,0]
	v_pk_mul_f32 v[58:59], v[56:57], v[56:57]
	v_pk_mul_f32 v[60:61], v[54:55], v[54:55]
	v_pk_fma_f32 v[58:59], v[58:59], s[12:13], v[146:147] op_sel_hi:[1,0,0] neg_lo:[1,0,0] neg_hi:[1,0,0]
	v_pk_fma_f32 v[60:61], v[60:61], s[12:13], v[146:147] op_sel_hi:[1,0,0] neg_lo:[1,0,0] neg_hi:[1,0,0]
	v_pk_fma_f32 v[64:65], v[64:65], s[12:13], v[146:147] op_sel_hi:[1,0,0] neg_lo:[1,0,0] neg_hi:[1,0,0]
	v_pk_mul_f32 v[60:61], v[54:55], v[60:61]
	v_pk_mul_f32 v[58:59], v[56:57], v[58:59]
	v_pk_mul_f32 v[64:65], v[50:51], v[64:65]
	v_pk_mul_f32 v[62:63], v[52:53], v[62:63]
	v_exp_f32_e32 v60, v60
	v_exp_f32_e32 v61, v61
	v_exp_f32_e32 v58, v58
	v_exp_f32_e32 v59, v59
	v_exp_f32_e32 v64, v64
	v_exp_f32_e32 v65, v65
	v_exp_f32_e32 v62, v62
	v_exp_f32_e32 v63, v63
	v_pk_add_f32 v[60:61], v[60:61], 1.0 op_sel_hi:[1,0]
	v_pk_add_f32 v[58:59], v[58:59], 1.0 op_sel_hi:[1,0]
	v_pk_add_f32 v[64:65], v[64:65], 1.0 op_sel_hi:[1,0]
	v_pk_add_f32 v[62:63], v[62:63], 1.0 op_sel_hi:[1,0]
	v_rcp_f32_e32 v60, v60
	v_rcp_f32_e32 v61, v61
	v_rcp_f32_e32 v58, v58
	v_rcp_f32_e32 v59, v59
	v_rcp_f32_e32 v64, v64
	v_rcp_f32_e32 v65, v65
	v_rcp_f32_e32 v62, v62
	v_rcp_f32_e32 v63, v63
	v_pk_mul_f32 v[54:55], v[54:55], v[60:61]
	v_pk_mul_f32 v[56:57], v[56:57], v[58:59]
	v_pk_mul_f32 v[58:59], v[50:51], v[64:65]
	v_pk_mul_f32 v[60:61], v[52:53], v[62:63]
	v_cvt_pk_bf16_f32 v50, v54, v55
	v_cvt_pk_bf16_f32 v51, v56, v57
	v_cvt_pk_bf16_f32 v52, v58, v59
	v_pk_mul_f32 v[54:55], v[46:47], v[46:47]
	v_cvt_pk_bf16_f32 v53, v60, v61
	global_store_dwordx4 v[66:67], v[50:53], off offset:256 sc1
	v_pk_mul_f32 v[56:57], v[44:45], v[44:45]
	v_pk_mul_f32 v[58:59], v[42:43], v[42:43]
	v_pk_mul_f32 v[52:53], v[48:49], v[48:49]
	v_pk_fma_f32 v[54:55], v[54:55], s[12:13], v[146:147] op_sel_hi:[1,0,0] neg_lo:[1,0,0] neg_hi:[1,0,0]
	v_pk_fma_f32 v[52:53], v[52:53], s[12:13], v[146:147] op_sel_hi:[1,0,0] neg_lo:[1,0,0] neg_hi:[1,0,0]
	v_pk_fma_f32 v[58:59], v[58:59], s[12:13], v[146:147] op_sel_hi:[1,0,0] neg_lo:[1,0,0] neg_hi:[1,0,0]
	v_pk_fma_f32 v[56:57], v[56:57], s[12:13], v[146:147] op_sel_hi:[1,0,0] neg_lo:[1,0,0] neg_hi:[1,0,0]
	v_pk_mul_f32 v[54:55], v[46:47], v[54:55]
	v_pk_mul_f32 v[52:53], v[48:49], v[52:53]
	v_pk_mul_f32 v[58:59], v[42:43], v[58:59]
	v_pk_mul_f32 v[56:57], v[44:45], v[56:57]
	v_exp_f32_e32 v54, v54
	v_exp_f32_e32 v55, v55
	v_exp_f32_e32 v52, v52
	v_exp_f32_e32 v53, v53
	v_exp_f32_e32 v58, v58
	v_exp_f32_e32 v59, v59
	v_exp_f32_e32 v56, v56
	v_exp_f32_e32 v57, v57
	v_pk_add_f32 v[54:55], v[54:55], 1.0 op_sel_hi:[1,0]
	v_pk_add_f32 v[52:53], v[52:53], 1.0 op_sel_hi:[1,0]
	v_pk_add_f32 v[58:59], v[58:59], 1.0 op_sel_hi:[1,0]
	v_pk_add_f32 v[56:57], v[56:57], 1.0 op_sel_hi:[1,0]
	v_rcp_f32_e32 v54, v54
	v_rcp_f32_e32 v55, v55
	v_rcp_f32_e32 v52, v52
	v_rcp_f32_e32 v53, v53
	v_rcp_f32_e32 v58, v58
	v_rcp_f32_e32 v59, v59
	v_rcp_f32_e32 v56, v56
	v_rcp_f32_e32 v57, v57
	v_add_u32_e32 v50, 0x90, v156
	v_mad_i64_i32 v[50:51], s[30:31], s28, v50, 0
	v_lshl_add_u64 v[50:51], v[50:51], 1, v[148:149]
	v_pk_mul_f32 v[46:47], v[46:47], v[54:55]
	v_pk_mul_f32 v[48:49], v[48:49], v[52:53]
	v_pk_mul_f32 v[52:53], v[42:43], v[58:59]
	v_pk_mul_f32 v[54:55], v[44:45], v[56:57]
	v_cvt_pk_bf16_f32 v42, v46, v47
	v_cvt_pk_bf16_f32 v43, v48, v49
	v_cvt_pk_bf16_f32 v44, v52, v53
	v_pk_mul_f32 v[46:47], v[36:37], v[36:37]
	v_cvt_pk_bf16_f32 v45, v54, v55
	global_store_dwordx4 v[50:51], v[42:45], off sc1
	v_pk_mul_f32 v[48:49], v[34:35], v[34:35]
	v_pk_fma_f32 v[46:47], v[46:47], s[12:13], v[146:147] op_sel_hi:[1,0,0] neg_lo:[1,0,0] neg_hi:[1,0,0]
	v_pk_mul_f32 v[42:43], v[40:41], v[40:41]
	v_pk_mul_f32 v[44:45], v[38:39], v[38:39]
	v_pk_fma_f32 v[42:43], v[42:43], s[12:13], v[146:147] op_sel_hi:[1,0,0] neg_lo:[1,0,0] neg_hi:[1,0,0]
	v_pk_fma_f32 v[44:45], v[44:45], s[12:13], v[146:147] op_sel_hi:[1,0,0] neg_lo:[1,0,0] neg_hi:[1,0,0]
	v_pk_fma_f32 v[48:49], v[48:49], s[12:13], v[146:147] op_sel_hi:[1,0,0] neg_lo:[1,0,0] neg_hi:[1,0,0]
	v_pk_mul_f32 v[44:45], v[38:39], v[44:45]
	v_pk_mul_f32 v[42:43], v[40:41], v[42:43]
	v_pk_mul_f32 v[48:49], v[34:35], v[48:49]
	v_pk_mul_f32 v[46:47], v[36:37], v[46:47]
	v_exp_f32_e32 v44, v44
	v_exp_f32_e32 v45, v45
	v_exp_f32_e32 v42, v42
	v_exp_f32_e32 v43, v43
	v_exp_f32_e32 v48, v48
	v_exp_f32_e32 v49, v49
	v_exp_f32_e32 v46, v46
	v_exp_f32_e32 v47, v47
	v_pk_add_f32 v[44:45], v[44:45], 1.0 op_sel_hi:[1,0]
	v_pk_add_f32 v[42:43], v[42:43], 1.0 op_sel_hi:[1,0]
	v_pk_add_f32 v[48:49], v[48:49], 1.0 op_sel_hi:[1,0]
	v_pk_add_f32 v[46:47], v[46:47], 1.0 op_sel_hi:[1,0]
	v_rcp_f32_e32 v44, v44
	v_rcp_f32_e32 v45, v45
	v_rcp_f32_e32 v42, v42
	v_rcp_f32_e32 v43, v43
	v_rcp_f32_e32 v48, v48
	v_rcp_f32_e32 v49, v49
	v_rcp_f32_e32 v46, v46
	v_rcp_f32_e32 v47, v47
	v_pk_mul_f32 v[38:39], v[38:39], v[44:45]
	v_pk_mul_f32 v[40:41], v[40:41], v[42:43]
	v_pk_mul_f32 v[42:43], v[34:35], v[48:49]
	v_pk_mul_f32 v[44:45], v[36:37], v[46:47]
	v_cvt_pk_bf16_f32 v34, v38, v39
	v_cvt_pk_bf16_f32 v35, v40, v41
	v_cvt_pk_bf16_f32 v36, v42, v43
	v_pk_mul_f32 v[38:39], v[30:31], v[30:31]
	v_cvt_pk_bf16_f32 v37, v44, v45
	global_store_dwordx4 v[50:51], v[34:37], off offset:256 sc1
	v_pk_mul_f32 v[40:41], v[28:29], v[28:29]
	v_pk_mul_f32 v[42:43], v[26:27], v[26:27]
	v_pk_mul_f32 v[36:37], v[32:33], v[32:33]
	v_pk_fma_f32 v[38:39], v[38:39], s[12:13], v[146:147] op_sel_hi:[1,0,0] neg_lo:[1,0,0] neg_hi:[1,0,0]
	v_pk_fma_f32 v[36:37], v[36:37], s[12:13], v[146:147] op_sel_hi:[1,0,0] neg_lo:[1,0,0] neg_hi:[1,0,0]
	v_pk_fma_f32 v[42:43], v[42:43], s[12:13], v[146:147] op_sel_hi:[1,0,0] neg_lo:[1,0,0] neg_hi:[1,0,0]
	v_pk_fma_f32 v[40:41], v[40:41], s[12:13], v[146:147] op_sel_hi:[1,0,0] neg_lo:[1,0,0] neg_hi:[1,0,0]
	v_pk_mul_f32 v[38:39], v[30:31], v[38:39]
	v_pk_mul_f32 v[36:37], v[32:33], v[36:37]
	v_pk_mul_f32 v[42:43], v[26:27], v[42:43]
	v_pk_mul_f32 v[40:41], v[28:29], v[40:41]
	v_exp_f32_e32 v38, v38
	v_exp_f32_e32 v39, v39
	v_exp_f32_e32 v36, v36
	v_exp_f32_e32 v37, v37
	v_exp_f32_e32 v42, v42
	v_exp_f32_e32 v43, v43
	v_exp_f32_e32 v40, v40
	v_exp_f32_e32 v41, v41
	v_pk_add_f32 v[38:39], v[38:39], 1.0 op_sel_hi:[1,0]
	v_pk_add_f32 v[36:37], v[36:37], 1.0 op_sel_hi:[1,0]
	v_pk_add_f32 v[42:43], v[42:43], 1.0 op_sel_hi:[1,0]
	v_pk_add_f32 v[40:41], v[40:41], 1.0 op_sel_hi:[1,0]
	v_rcp_f32_e32 v38, v38
	v_rcp_f32_e32 v39, v39
	v_rcp_f32_e32 v36, v36
	v_rcp_f32_e32 v37, v37
	v_rcp_f32_e32 v42, v42
	v_rcp_f32_e32 v43, v43
	v_rcp_f32_e32 v40, v40
	v_rcp_f32_e32 v41, v41
	v_add_u32_e32 v34, 0xa0, v156
	v_mad_i64_i32 v[34:35], s[30:31], s28, v34, 0
	v_lshl_add_u64 v[34:35], v[34:35], 1, v[148:149]
	v_pk_mul_f32 v[30:31], v[30:31], v[38:39]
	v_pk_mul_f32 v[32:33], v[32:33], v[36:37]
	v_pk_mul_f32 v[36:37], v[26:27], v[42:43]
	v_pk_mul_f32 v[38:39], v[28:29], v[40:41]
	v_cvt_pk_bf16_f32 v26, v30, v31
	v_cvt_pk_bf16_f32 v27, v32, v33
	v_cvt_pk_bf16_f32 v28, v36, v37
	v_pk_mul_f32 v[30:31], v[20:21], v[20:21]
	v_cvt_pk_bf16_f32 v29, v38, v39
	global_store_dwordx4 v[34:35], v[26:29], off sc1
	v_pk_mul_f32 v[32:33], v[18:19], v[18:19]
	v_pk_fma_f32 v[30:31], v[30:31], s[12:13], v[146:147] op_sel_hi:[1,0,0] neg_lo:[1,0,0] neg_hi:[1,0,0]
	v_pk_mul_f32 v[26:27], v[24:25], v[24:25]
	v_pk_mul_f32 v[28:29], v[22:23], v[22:23]
	v_pk_fma_f32 v[26:27], v[26:27], s[12:13], v[146:147] op_sel_hi:[1,0,0] neg_lo:[1,0,0] neg_hi:[1,0,0]
	v_pk_fma_f32 v[28:29], v[28:29], s[12:13], v[146:147] op_sel_hi:[1,0,0] neg_lo:[1,0,0] neg_hi:[1,0,0]
	v_pk_fma_f32 v[32:33], v[32:33], s[12:13], v[146:147] op_sel_hi:[1,0,0] neg_lo:[1,0,0] neg_hi:[1,0,0]
	v_pk_mul_f32 v[28:29], v[22:23], v[28:29]
	v_pk_mul_f32 v[26:27], v[24:25], v[26:27]
	v_pk_mul_f32 v[32:33], v[18:19], v[32:33]
	v_pk_mul_f32 v[30:31], v[20:21], v[30:31]
	v_exp_f32_e32 v28, v28
	v_exp_f32_e32 v29, v29
	v_exp_f32_e32 v26, v26
	v_exp_f32_e32 v27, v27
	v_exp_f32_e32 v32, v32
	v_exp_f32_e32 v33, v33
	v_exp_f32_e32 v30, v30
	v_exp_f32_e32 v31, v31
	v_pk_add_f32 v[28:29], v[28:29], 1.0 op_sel_hi:[1,0]
	v_pk_add_f32 v[26:27], v[26:27], 1.0 op_sel_hi:[1,0]
	v_pk_add_f32 v[32:33], v[32:33], 1.0 op_sel_hi:[1,0]
	v_pk_add_f32 v[30:31], v[30:31], 1.0 op_sel_hi:[1,0]
	v_rcp_f32_e32 v28, v28
	v_rcp_f32_e32 v29, v29
	v_rcp_f32_e32 v26, v26
	v_rcp_f32_e32 v27, v27
	v_rcp_f32_e32 v32, v32
	v_rcp_f32_e32 v33, v33
	v_rcp_f32_e32 v30, v30
	v_rcp_f32_e32 v31, v31
	v_pk_mul_f32 v[22:23], v[22:23], v[28:29]
	v_pk_mul_f32 v[24:25], v[24:25], v[26:27]
	v_pk_mul_f32 v[26:27], v[18:19], v[32:33]
	v_pk_mul_f32 v[28:29], v[20:21], v[30:31]
	v_cvt_pk_bf16_f32 v18, v22, v23
	v_cvt_pk_bf16_f32 v19, v24, v25
	v_cvt_pk_bf16_f32 v20, v26, v27
	v_pk_mul_f32 v[22:23], v[14:15], v[14:15]
	v_cvt_pk_bf16_f32 v21, v28, v29
	global_store_dwordx4 v[34:35], v[18:21], off offset:256 sc1
	v_pk_mul_f32 v[24:25], v[12:13], v[12:13]
	v_pk_mul_f32 v[26:27], v[10:11], v[10:11]
	v_pk_mul_f32 v[20:21], v[16:17], v[16:17]
	v_pk_fma_f32 v[22:23], v[22:23], s[12:13], v[146:147] op_sel_hi:[1,0,0] neg_lo:[1,0,0] neg_hi:[1,0,0]
	v_pk_fma_f32 v[20:21], v[20:21], s[12:13], v[146:147] op_sel_hi:[1,0,0] neg_lo:[1,0,0] neg_hi:[1,0,0]
	v_pk_fma_f32 v[26:27], v[26:27], s[12:13], v[146:147] op_sel_hi:[1,0,0] neg_lo:[1,0,0] neg_hi:[1,0,0]
	v_pk_fma_f32 v[24:25], v[24:25], s[12:13], v[146:147] op_sel_hi:[1,0,0] neg_lo:[1,0,0] neg_hi:[1,0,0]
	v_pk_mul_f32 v[22:23], v[14:15], v[22:23]
	v_pk_mul_f32 v[20:21], v[16:17], v[20:21]
	v_pk_mul_f32 v[26:27], v[10:11], v[26:27]
	v_pk_mul_f32 v[24:25], v[12:13], v[24:25]
	v_exp_f32_e32 v22, v22
	v_exp_f32_e32 v23, v23
	v_exp_f32_e32 v20, v20
	v_exp_f32_e32 v21, v21
	v_exp_f32_e32 v26, v26
	v_exp_f32_e32 v27, v27
	v_exp_f32_e32 v24, v24
	v_exp_f32_e32 v25, v25
	v_pk_add_f32 v[22:23], v[22:23], 1.0 op_sel_hi:[1,0]
	v_pk_add_f32 v[20:21], v[20:21], 1.0 op_sel_hi:[1,0]
	v_pk_add_f32 v[26:27], v[26:27], 1.0 op_sel_hi:[1,0]
	v_pk_add_f32 v[24:25], v[24:25], 1.0 op_sel_hi:[1,0]
	v_rcp_f32_e32 v22, v22
	v_rcp_f32_e32 v23, v23
	v_rcp_f32_e32 v20, v20
	v_rcp_f32_e32 v21, v21
	v_rcp_f32_e32 v26, v26
	v_rcp_f32_e32 v27, v27
	v_rcp_f32_e32 v24, v24
	v_rcp_f32_e32 v25, v25
	v_add_u32_e32 v18, 0xb0, v156
	v_mad_i64_i32 v[18:19], s[28:29], s28, v18, 0
	v_lshl_add_u64 v[18:19], v[18:19], 1, v[148:149]
	v_pk_mul_f32 v[14:15], v[14:15], v[22:23]
	v_pk_mul_f32 v[16:17], v[16:17], v[20:21]
	v_pk_mul_f32 v[20:21], v[10:11], v[26:27]
	v_pk_mul_f32 v[22:23], v[12:13], v[24:25]
	v_cvt_pk_bf16_f32 v10, v14, v15
	v_cvt_pk_bf16_f32 v11, v16, v17
	v_cvt_pk_bf16_f32 v12, v20, v21
	v_pk_mul_f32 v[14:15], v[4:5], v[4:5]
	v_cvt_pk_bf16_f32 v13, v22, v23
	global_store_dwordx4 v[18:19], v[10:13], off sc1
	v_pk_mul_f32 v[16:17], v[2:3], v[2:3]
	v_pk_fma_f32 v[14:15], v[14:15], s[12:13], v[146:147] op_sel_hi:[1,0,0] neg_lo:[1,0,0] neg_hi:[1,0,0]
	v_pk_mul_f32 v[10:11], v[8:9], v[8:9]
	v_pk_mul_f32 v[12:13], v[6:7], v[6:7]
	v_pk_fma_f32 v[10:11], v[10:11], s[12:13], v[146:147] op_sel_hi:[1,0,0] neg_lo:[1,0,0] neg_hi:[1,0,0]
	v_pk_fma_f32 v[12:13], v[12:13], s[12:13], v[146:147] op_sel_hi:[1,0,0] neg_lo:[1,0,0] neg_hi:[1,0,0]
	v_pk_fma_f32 v[16:17], v[16:17], s[12:13], v[146:147] op_sel_hi:[1,0,0] neg_lo:[1,0,0] neg_hi:[1,0,0]
	v_pk_mul_f32 v[12:13], v[6:7], v[12:13]
	v_pk_mul_f32 v[10:11], v[8:9], v[10:11]
	v_pk_mul_f32 v[16:17], v[2:3], v[16:17]
	v_pk_mul_f32 v[14:15], v[4:5], v[14:15]
	v_exp_f32_e32 v12, v12
	v_exp_f32_e32 v13, v13
	v_exp_f32_e32 v10, v10
	v_exp_f32_e32 v11, v11
	v_exp_f32_e32 v16, v16
	v_exp_f32_e32 v17, v17
	v_exp_f32_e32 v14, v14
	v_exp_f32_e32 v15, v15
	v_pk_add_f32 v[12:13], v[12:13], 1.0 op_sel_hi:[1,0]
	v_pk_add_f32 v[10:11], v[10:11], 1.0 op_sel_hi:[1,0]
	v_pk_add_f32 v[16:17], v[16:17], 1.0 op_sel_hi:[1,0]
	v_pk_add_f32 v[14:15], v[14:15], 1.0 op_sel_hi:[1,0]
	v_rcp_f32_e32 v12, v12
	v_rcp_f32_e32 v13, v13
	v_rcp_f32_e32 v10, v10
	v_rcp_f32_e32 v11, v11
	v_rcp_f32_e32 v16, v16
	v_rcp_f32_e32 v17, v17
	v_rcp_f32_e32 v14, v14
	v_rcp_f32_e32 v15, v15
	s_andn2_b64 vcc, exec, s[0:1]
	s_mov_b64 s[0:1], -1
	v_pk_mul_f32 v[6:7], v[6:7], v[12:13]
	v_pk_mul_f32 v[8:9], v[8:9], v[10:11]
	v_pk_mul_f32 v[10:11], v[2:3], v[16:17]
	v_pk_mul_f32 v[12:13], v[4:5], v[14:15]
	v_cvt_pk_bf16_f32 v2, v6, v7
	v_cvt_pk_bf16_f32 v3, v8, v9
	v_cvt_pk_bf16_f32 v4, v10, v11
	s_nop 0
	v_cvt_pk_bf16_f32 v5, v12, v13
	global_store_dwordx4 v[18:19], v[2:5], off offset:256 sc1
	s_cbranch_vccnz .LBB0_3007
	s_andn2_b64 vcc, exec, s[6:7]
	s_cbranch_vccnz .LBB0_3006
	s_barrier
	s_branch .LBB0_3006
